# SwiGLU epilogue: adjacent lanes exchange bf16 halves (DPP quad_perm + v_perm) and write G with dword stores instead of twice as many short stores
# speedup vs baseline: 1.0032x; 1.0032x over previous
; DI int get_tid() { int t = threadIdx.x; asm volatile("" : "+v"(t)); return t; }
; template <int EPI>
; DI void gemm_phase(const Params& p, int layer, const bf16_t* __restrict__ A, int lda, const bf16_t* __restrict__ Bt, int ldb, int K, int MT, int NT,
;                    char* smem, bool rev = false) {
;     ...
;   const int tid = get_tid(), lane = tid & 63, wave = tid >> 6, wr = wave >> 1, wc = wave & 1;
;   const int total = MT * NT;
;   int t = rev ? (int)(gridDim.x - 1 - blockIdx.x) : (int)blockIdx.x;
;   if (t >= total) return;
;   uint4 pa0, pa1, pa2, pa3, pb0, pb1, pb2, pb3, qa0, qa1, qa2, qa3, qb0, qb1, qb2, qb3;
;   const int lr = tid >> 3, lc = (tid & 7) * 8;
;   const int nk = K >> 6;
;   const int soff = lr * LDT + lc;
;   const int aoff = (wr * 64 + (lane & 31)) * LDT + (lane >> 5) * 8;
;   const int boff = (wc * 64 + (lane & 31)) * LDT + (lane >> 5) * 8;
;   int mt, nt; tile_map(t, MT, NT, mt, nt);
;   int m0 = mt * 128, n0 = nt * 128;
;   const bf16_t* Agl = A + (size_t)(m0 + lr) * lda + lc;
;   const bf16_t* Bgl = Bt + (size_t)(n0 + lr) * ldb + lc;
.Lmg_pare_9:
	s_lshl_b32 s0, s61, 3
	s_mul_i32 s64, s0, s62
	v_lshrrev_b32_e32 v184, 2, v140
	v_and_b32_e32 v185, 3, v140
	v_bfe_u32 v186, v140, 4, 2
	v_xor_b32_e32 v185, v185, v186
	v_lshlrev_b32_e32 v185, 4, v185
	s_lshl_b32 s0, s77, 6
	v_add_u32_e32 v186, s0, v184
	v_mul_lo_u32 v186, v186, s58
	v_add_u32_e32 v213, v186, v185
	s_lshl_b32 s0, s58, 4
	s_sub_u32 s0, s0, 0x400
	v_add_u32_e32 v214, s0, v213
	v_add_u32_e32 v215, s0, v214
	v_add_u32_e32 v216, s0, v215
	s_lshl_b32 s0, s77, 5
	v_add_u32_e32 v186, s0, v184
	v_mul_lo_u32 v186, v186, s59
	v_add_u32_e32 v217, v186, v185
	s_lshl_b32 s0, s59, 4
	s_sub_u32 s0, s0, 0x400
	v_add_u32_e32 v218, s0, v217
	v_bfe_u32 v184, v140, 2, 2
	v_xor_b32_e32 v185, v184, v228
	v_xor_b32_e32 v186, 2, v185
	v_lshlrev_b32_e32 v187, 6, v227
	v_lshl_add_u32 v185, v185, 4, v187
	v_lshl_add_u32 v186, v186, 4, v187
	s_mul_i32 s0, s78, 0x3000
	v_add_u32_e32 v219, s0, v185
	v_add_u32_e32 v220, s0, v186
	s_mul_i32 s0, s79, 0x3000
	s_add_u32 s0, s0, 0x1000
	v_add_u32_e32 v221, s0, v185
	v_add_u32_e32 v222, s0, v186
	s_cmp_ge_u32 s66, s64
	s_cbranch_scc1 .Lmg_done

; DI bf16_t f2bf(float x) { return (bf16_t)(pack2(x, x) & 0xffffu); }
; DI int crow(int reg, int h) { return (reg & 3) + 8 * (reg >> 2) + 4 * h; }
; DI float silu_f(float x) { return x * __builtin_amdgcn_rcpf(1.0f + __expf(-x)); }
; template <int EPI>
; DI void epilogue(const Params& p, int layer, f32x16 (&acc)[2][2], int mrow0, int ncol0, int lane) {
;     ...
;   } else if (EPI == EPI_SWIGLU) {
;     bf16_t* G = (bf16_t*)(p.ws + OFF_U);
;     const int j = (ncol0 >> 7) * 64 + ((ncol0 >> 6) & 1) * 32 + c;
; #pragma unroll
;     for (int mi = 0; mi < 2; ++mi)
; #pragma unroll
;       for (int r = 0; r < 16; ++r) {
;         int row = mrow0 + mi * 32 + crow(r, h);
;         float a1 = acc[mi][0][r], a3 = acc[mi][1][r];
;         G[(size_t)row * FFH + j] = f2bf(silu_f(a1) * a3);
;       }
.Lmg_epi2:
	s_lshl_b32 s90, s78, 7
	s_add_u32 s90, s90, s67
	s_lshl_b32 s91, s79, 6
	s_add_u32 s91, s91, s68
	s_mov_b32 s82, s24
	s_mov_b32 s83, s25
	s_lshr_b32 s1, s68, 7
	s_lshl_b32 s1, s1, 1
	s_add_u32 s1, s1, s79
	s_mul_i32 s1, s1, 0x8800
	s_add_u32 s1, s1, s90
	v_lshl_add_u32 v184, v228, 2, s1
	v_lshlrev_b32_e32 v184, 6, v184
	v_and_b32_e32 v185, 1, v227
	v_sub_u32_e32 v186, v227, v185
	v_lshl_add_u32 v229, v186, 1, v184
	s_movk_i32 s45, 64
	v_mad_u32_u24 v229, v185, s45, v229
	v_mov_b32_e32 v230, 0x05040100
	v_mov_b32_e32 v186, 0x03020706
	v_cmp_eq_u32_e32 vcc, 1, v185
	s_nop 1
	v_cndmask_b32_e32 v230, v230, v186, vcc
	v_mov_b32_e32 v148, v229
	v_mul_f32_e32 v144, 0xbfb8aa3b, v0
	v_mul_f32_e32 v145, 0xbfb8aa3b, v1
	v_mul_f32_e32 v146, 0xbfb8aa3b, v2
	v_mul_f32_e32 v147, 0xbfb8aa3b, v3
	v_exp_f32_e32 v144, v144
	v_exp_f32_e32 v145, v145
	v_exp_f32_e32 v146, v146
	v_exp_f32_e32 v147, v147
	s_nop 1
	v_add_f32_e32 v144, 1.0, v144
	v_add_f32_e32 v145, 1.0, v145
	v_add_f32_e32 v146, 1.0, v146
	v_add_f32_e32 v147, 1.0, v147
	v_rcp_f32_e32 v144, v144
	v_rcp_f32_e32 v145, v145
	v_rcp_f32_e32 v146, v146
	v_rcp_f32_e32 v147, v147
	s_nop 0
	v_mul_f32_e32 v144, v0, v144
	v_mul_f32_e32 v145, v1, v145
	v_mul_f32_e32 v146, v2, v146
	v_mul_f32_e32 v147, v3, v147
	v_mul_f32_e32 v144, v16, v144
	v_mul_f32_e32 v145, v17, v145
	v_mul_f32_e32 v146, v18, v146
	v_mul_f32_e32 v147, v19, v147
	v_cvt_pk_bf16_f32 v152, v144, v145
	v_cvt_pk_bf16_f32 v153, v146, v147
	s_nop 0
	v_mov_b32_dpp v144, v152 quad_perm:[1,0,3,2] row_mask:0xf bank_mask:0xf
	v_mov_b32_dpp v145, v153 quad_perm:[1,0,3,2] row_mask:0xf bank_mask:0xf
	v_perm_b32 v152, v144, v152, v230
	v_perm_b32 v153, v145, v153, v230
	global_store_dword v148, v152, s[82:83]
	global_store_dword v148, v153, s[82:83] offset:128
	v_mul_f32_e32 v144, 0xbfb8aa3b, v4
	v_mul_f32_e32 v145, 0xbfb8aa3b, v5
	v_mul_f32_e32 v146, 0xbfb8aa3b, v6
	v_mul_f32_e32 v147, 0xbfb8aa3b, v7
	v_exp_f32_e32 v144, v144
	v_exp_f32_e32 v145, v145
	v_exp_f32_e32 v146, v146
	v_exp_f32_e32 v147, v147
	s_nop 1
	v_add_f32_e32 v144, 1.0, v144
	v_add_f32_e32 v145, 1.0, v145
	v_add_f32_e32 v146, 1.0, v146
	v_add_f32_e32 v147, 1.0, v147
	v_rcp_f32_e32 v144, v144
	v_rcp_f32_e32 v145, v145
	v_rcp_f32_e32 v146, v146
	v_rcp_f32_e32 v147, v147
	s_nop 0
	v_mul_f32_e32 v144, v4, v144
	v_mul_f32_e32 v145, v5, v145
	v_mul_f32_e32 v146, v6, v146
	v_mul_f32_e32 v147, v7, v147
	v_mul_f32_e32 v144, v20, v144
	v_mul_f32_e32 v145, v21, v145
	v_mul_f32_e32 v146, v22, v146
	v_mul_f32_e32 v147, v23, v147
	v_cvt_pk_bf16_f32 v154, v144, v145
	v_cvt_pk_bf16_f32 v155, v146, v147
	s_nop 0
	v_mov_b32_dpp v144, v154 quad_perm:[1,0,3,2] row_mask:0xf bank_mask:0xf
	v_mov_b32_dpp v145, v155 quad_perm:[1,0,3,2] row_mask:0xf bank_mask:0xf
	v_perm_b32 v154, v144, v154, v230
	v_perm_b32 v155, v145, v155, v230
	global_store_dword v148, v154, s[82:83] offset:512
	global_store_dword v148, v155, s[82:83] offset:640
	v_mul_f32_e32 v144, 0xbfb8aa3b, v8
	v_mul_f32_e32 v145, 0xbfb8aa3b, v9
	v_mul_f32_e32 v146, 0xbfb8aa3b, v10
	v_mul_f32_e32 v147, 0xbfb8aa3b, v11
	v_exp_f32_e32 v144, v144
	v_exp_f32_e32 v145, v145
	v_exp_f32_e32 v146, v146
	v_exp_f32_e32 v147, v147
	s_nop 1
	v_add_f32_e32 v144, 1.0, v144
	v_add_f32_e32 v145, 1.0, v145
	v_add_f32_e32 v146, 1.0, v146
	v_add_f32_e32 v147, 1.0, v147
	v_rcp_f32_e32 v144, v144
	v_rcp_f32_e32 v145, v145
	v_rcp_f32_e32 v146, v146
	v_rcp_f32_e32 v147, v147
	s_nop 0
	v_mul_f32_e32 v144, v8, v144
	v_mul_f32_e32 v145, v9, v145
	v_mul_f32_e32 v146, v10, v146
	v_mul_f32_e32 v147, v11, v147
	v_mul_f32_e32 v144, v24, v144
	v_mul_f32_e32 v145, v25, v145
	v_mul_f32_e32 v146, v26, v146
	v_mul_f32_e32 v147, v27, v147
	v_cvt_pk_bf16_f32 v152, v144, v145
	v_cvt_pk_bf16_f32 v153, v146, v147
	s_nop 0
	v_mov_b32_dpp v144, v152 quad_perm:[1,0,3,2] row_mask:0xf bank_mask:0xf
	v_mov_b32_dpp v145, v153 quad_perm:[1,0,3,2] row_mask:0xf bank_mask:0xf
	v_perm_b32 v152, v144, v152, v230
	v_perm_b32 v153, v145, v153, v230
	global_store_dword v148, v152, s[82:83] offset:1024
	global_store_dword v148, v153, s[82:83] offset:1152
	v_mul_f32_e32 v144, 0xbfb8aa3b, v12
	v_mul_f32_e32 v145, 0xbfb8aa3b, v13
	v_mul_f32_e32 v146, 0xbfb8aa3b, v14
	v_mul_f32_e32 v147, 0xbfb8aa3b, v15
	v_exp_f32_e32 v144, v144
	v_exp_f32_e32 v145, v145
	v_exp_f32_e32 v146, v146
	v_exp_f32_e32 v147, v147
	s_nop 1
	v_add_f32_e32 v144, 1.0, v144
	v_add_f32_e32 v145, 1.0, v145
	v_add_f32_e32 v146, 1.0, v146
	v_add_f32_e32 v147, 1.0, v147
	v_rcp_f32_e32 v144, v144
	v_rcp_f32_e32 v145, v145
	v_rcp_f32_e32 v146, v146
	v_rcp_f32_e32 v147, v147
	s_nop 0
	v_mul_f32_e32 v144, v12, v144
	v_mul_f32_e32 v145, v13, v145
	v_mul_f32_e32 v146, v14, v146
	v_mul_f32_e32 v147, v15, v147
	v_mul_f32_e32 v144, v28, v144
	v_mul_f32_e32 v145, v29, v145
	v_mul_f32_e32 v146, v30, v146
	v_mul_f32_e32 v147, v31, v147
	v_cvt_pk_bf16_f32 v154, v144, v145
	v_cvt_pk_bf16_f32 v155, v146, v147
	s_nop 0
	v_mov_b32_dpp v144, v154 quad_perm:[1,0,3,2] row_mask:0xf bank_mask:0xf
	v_mov_b32_dpp v145, v155 quad_perm:[1,0,3,2] row_mask:0xf bank_mask:0xf
	v_perm_b32 v154, v144, v154, v230
	v_perm_b32 v155, v145, v155, v230
	global_store_dword v148, v154, s[82:83] offset:1536
	global_store_dword v148, v155, s[82:83] offset:1664
	v_add_u32_e32 v148, 0x800, v229
	v_mul_f32_e32 v144, 0xbfb8aa3b, v32
	v_mul_f32_e32 v145, 0xbfb8aa3b, v33
	v_mul_f32_e32 v146, 0xbfb8aa3b, v34
	v_mul_f32_e32 v147, 0xbfb8aa3b, v35
	v_exp_f32_e32 v144, v144
	v_exp_f32_e32 v145, v145
	v_exp_f32_e32 v146, v146
	v_exp_f32_e32 v147, v147
	s_nop 1
	v_add_f32_e32 v144, 1.0, v144
	v_add_f32_e32 v145, 1.0, v145
	v_add_f32_e32 v146, 1.0, v146
	v_add_f32_e32 v147, 1.0, v147
; DI bf16_t f2bf(float x) { return (bf16_t)(pack2(x, x) & 0xffffu); }
; DI int crow(int reg, int h) { return (reg & 3) + 8 * (reg >> 2) + 4 * h; }
; DI float silu_f(float x) { return x * __builtin_amdgcn_rcpf(1.0f + __expf(-x)); }
; template <int EPI>
; DI void epilogue(const Params& p, int layer, f32x16 (&acc)[2][2], int mrow0, int ncol0, int lane) {
;     ...
;   } else if (EPI == EPI_SWIGLU) {
;     bf16_t* G = (bf16_t*)(p.ws + OFF_U);
;     const int j = (ncol0 >> 7) * 64 + ((ncol0 >> 6) & 1) * 32 + c;
; #pragma unroll
;     for (int mi = 0; mi < 2; ++mi)
; #pragma unroll
;       for (int r = 0; r < 16; ++r) {
;         int row = mrow0 + mi * 32 + crow(r, h);
;         float a1 = acc[mi][0][r], a3 = acc[mi][1][r];
;         G[(size_t)row * FFH + j] = f2bf(silu_f(a1) * a3);
;       }
	v_rcp_f32_e32 v144, v144
	v_rcp_f32_e32 v145, v145
	v_rcp_f32_e32 v146, v146
	v_rcp_f32_e32 v147, v147
	s_nop 0
	v_mul_f32_e32 v144, v32, v144
	v_mul_f32_e32 v145, v33, v145
	v_mul_f32_e32 v146, v34, v146
	v_mul_f32_e32 v147, v35, v147
	v_mul_f32_e32 v144, v48, v144
	v_mul_f32_e32 v145, v49, v145
	v_mul_f32_e32 v146, v50, v146
	v_mul_f32_e32 v147, v51, v147
	v_cvt_pk_bf16_f32 v152, v144, v145
	v_cvt_pk_bf16_f32 v153, v146, v147
	s_nop 0
	v_mov_b32_dpp v144, v152 quad_perm:[1,0,3,2] row_mask:0xf bank_mask:0xf
	v_mov_b32_dpp v145, v153 quad_perm:[1,0,3,2] row_mask:0xf bank_mask:0xf
	v_perm_b32 v152, v144, v152, v230
	v_perm_b32 v153, v145, v153, v230
	global_store_dword v148, v152, s[82:83]
	global_store_dword v148, v153, s[82:83] offset:128
	v_mul_f32_e32 v144, 0xbfb8aa3b, v36
	v_mul_f32_e32 v145, 0xbfb8aa3b, v37
	v_mul_f32_e32 v146, 0xbfb8aa3b, v38
	v_mul_f32_e32 v147, 0xbfb8aa3b, v39
	v_exp_f32_e32 v144, v144
	v_exp_f32_e32 v145, v145
	v_exp_f32_e32 v146, v146
	v_exp_f32_e32 v147, v147
	s_nop 1
	v_add_f32_e32 v144, 1.0, v144
	v_add_f32_e32 v145, 1.0, v145
	v_add_f32_e32 v146, 1.0, v146
	v_add_f32_e32 v147, 1.0, v147
	v_rcp_f32_e32 v144, v144
	v_rcp_f32_e32 v145, v145
	v_rcp_f32_e32 v146, v146
	v_rcp_f32_e32 v147, v147
	s_nop 0
	v_mul_f32_e32 v144, v36, v144
	v_mul_f32_e32 v145, v37, v145
	v_mul_f32_e32 v146, v38, v146
	v_mul_f32_e32 v147, v39, v147
	v_mul_f32_e32 v144, v52, v144
	v_mul_f32_e32 v145, v53, v145
	v_mul_f32_e32 v146, v54, v146
	v_mul_f32_e32 v147, v55, v147
	v_cvt_pk_bf16_f32 v154, v144, v145
	v_cvt_pk_bf16_f32 v155, v146, v147
	s_nop 0
	v_mov_b32_dpp v144, v154 quad_perm:[1,0,3,2] row_mask:0xf bank_mask:0xf
	v_mov_b32_dpp v145, v155 quad_perm:[1,0,3,2] row_mask:0xf bank_mask:0xf
	v_perm_b32 v154, v144, v154, v230
	v_perm_b32 v155, v145, v155, v230
	global_store_dword v148, v154, s[82:83] offset:512
	global_store_dword v148, v155, s[82:83] offset:640
	v_mul_f32_e32 v144, 0xbfb8aa3b, v40
	v_mul_f32_e32 v145, 0xbfb8aa3b, v41
	v_mul_f32_e32 v146, 0xbfb8aa3b, v42
	v_mul_f32_e32 v147, 0xbfb8aa3b, v43
	v_exp_f32_e32 v144, v144
	v_exp_f32_e32 v145, v145
	v_exp_f32_e32 v146, v146
	v_exp_f32_e32 v147, v147
	s_nop 1
	v_add_f32_e32 v144, 1.0, v144
	v_add_f32_e32 v145, 1.0, v145
	v_add_f32_e32 v146, 1.0, v146
	v_add_f32_e32 v147, 1.0, v147
	v_rcp_f32_e32 v144, v144
	v_rcp_f32_e32 v145, v145
	v_rcp_f32_e32 v146, v146
	v_rcp_f32_e32 v147, v147
	s_nop 0
	v_mul_f32_e32 v144, v40, v144
	v_mul_f32_e32 v145, v41, v145
	v_mul_f32_e32 v146, v42, v146
	v_mul_f32_e32 v147, v43, v147
	v_mul_f32_e32 v144, v56, v144
	v_mul_f32_e32 v145, v57, v145
	v_mul_f32_e32 v146, v58, v146
	v_mul_f32_e32 v147, v59, v147
	v_cvt_pk_bf16_f32 v152, v144, v145
	v_cvt_pk_bf16_f32 v153, v146, v147
	s_nop 0
	v_mov_b32_dpp v144, v152 quad_perm:[1,0,3,2] row_mask:0xf bank_mask:0xf
	v_mov_b32_dpp v145, v153 quad_perm:[1,0,3,2] row_mask:0xf bank_mask:0xf
	v_perm_b32 v152, v144, v152, v230
	v_perm_b32 v153, v145, v153, v230
	global_store_dword v148, v152, s[82:83] offset:1024
	global_store_dword v148, v153, s[82:83] offset:1152
	v_mul_f32_e32 v144, 0xbfb8aa3b, v44
	v_mul_f32_e32 v145, 0xbfb8aa3b, v45
	v_mul_f32_e32 v146, 0xbfb8aa3b, v46
	v_mul_f32_e32 v147, 0xbfb8aa3b, v47
	v_exp_f32_e32 v144, v144
	v_exp_f32_e32 v145, v145
	v_exp_f32_e32 v146, v146
	v_exp_f32_e32 v147, v147
	s_nop 1
	v_add_f32_e32 v144, 1.0, v144
	v_add_f32_e32 v145, 1.0, v145
	v_add_f32_e32 v146, 1.0, v146
	v_add_f32_e32 v147, 1.0, v147
	v_rcp_f32_e32 v144, v144
	v_rcp_f32_e32 v145, v145
	v_rcp_f32_e32 v146, v146
	v_rcp_f32_e32 v147, v147
	s_nop 0
	v_mul_f32_e32 v144, v44, v144
	v_mul_f32_e32 v145, v45, v145
	v_mul_f32_e32 v146, v46, v146
	v_mul_f32_e32 v147, v47, v147
	v_mul_f32_e32 v144, v60, v144
	v_mul_f32_e32 v145, v61, v145
	v_mul_f32_e32 v146, v62, v146
	v_mul_f32_e32 v147, v63, v147
	v_cvt_pk_bf16_f32 v154, v144, v145
	v_cvt_pk_bf16_f32 v155, v146, v147
	s_nop 0
	v_mov_b32_dpp v144, v154 quad_perm:[1,0,3,2] row_mask:0xf bank_mask:0xf
	v_mov_b32_dpp v145, v155 quad_perm:[1,0,3,2] row_mask:0xf bank_mask:0xf
	v_perm_b32 v154, v144, v154, v230
	v_perm_b32 v155, v145, v155, v230
	global_store_dword v148, v154, s[82:83] offset:1536
	global_store_dword v148, v155, s[82:83] offset:1664
	v_add_u32_e32 v148, 0x1000, v229
	v_mul_f32_e32 v144, 0xbfb8aa3b, v64
	v_mul_f32_e32 v145, 0xbfb8aa3b, v65
	v_mul_f32_e32 v146, 0xbfb8aa3b, v66
	v_mul_f32_e32 v147, 0xbfb8aa3b, v67
	v_exp_f32_e32 v144, v144
	v_exp_f32_e32 v145, v145
	v_exp_f32_e32 v146, v146
	v_exp_f32_e32 v147, v147
	s_nop 1
	v_add_f32_e32 v144, 1.0, v144
	v_add_f32_e32 v145, 1.0, v145
	v_add_f32_e32 v146, 1.0, v146
	v_add_f32_e32 v147, 1.0, v147
	v_rcp_f32_e32 v144, v144
	v_rcp_f32_e32 v145, v145
	v_rcp_f32_e32 v146, v146
	v_rcp_f32_e32 v147, v147
	s_nop 0
	v_mul_f32_e32 v144, v64, v144
	v_mul_f32_e32 v145, v65, v145
	v_mul_f32_e32 v146, v66, v146
	v_mul_f32_e32 v147, v67, v147
	v_mul_f32_e32 v144, v80, v144
	v_mul_f32_e32 v145, v81, v145
	v_mul_f32_e32 v146, v82, v146
	v_mul_f32_e32 v147, v83, v147
	v_cvt_pk_bf16_f32 v152, v144, v145
	v_cvt_pk_bf16_f32 v153, v146, v147
	s_nop 0
	v_mov_b32_dpp v144, v152 quad_perm:[1,0,3,2] row_mask:0xf bank_mask:0xf
	v_mov_b32_dpp v145, v153 quad_perm:[1,0,3,2] row_mask:0xf bank_mask:0xf
	v_perm_b32 v152, v144, v152, v230
	v_perm_b32 v153, v145, v153, v230
	global_store_dword v148, v152, s[82:83]
	global_store_dword v148, v153, s[82:83] offset:128
	v_mul_f32_e32 v144, 0xbfb8aa3b, v68
	v_mul_f32_e32 v145, 0xbfb8aa3b, v69
	v_mul_f32_e32 v146, 0xbfb8aa3b, v70
	v_mul_f32_e32 v147, 0xbfb8aa3b, v71
	v_exp_f32_e32 v144, v144
	v_exp_f32_e32 v145, v145
	v_exp_f32_e32 v146, v146
	v_exp_f32_e32 v147, v147
	s_nop 1
; DI bf16_t f2bf(float x) { return (bf16_t)(pack2(x, x) & 0xffffu); }
; DI int crow(int reg, int h) { return (reg & 3) + 8 * (reg >> 2) + 4 * h; }
; DI float silu_f(float x) { return x * __builtin_amdgcn_rcpf(1.0f + __expf(-x)); }
; template <int EPI>
; DI void epilogue(const Params& p, int layer, f32x16 (&acc)[2][2], int mrow0, int ncol0, int lane) {
;     ...
;   } else if (EPI == EPI_SWIGLU) {
;     bf16_t* G = (bf16_t*)(p.ws + OFF_U);
;     const int j = (ncol0 >> 7) * 64 + ((ncol0 >> 6) & 1) * 32 + c;
; #pragma unroll
;     for (int mi = 0; mi < 2; ++mi)
; #pragma unroll
;       for (int r = 0; r < 16; ++r) {
;         int row = mrow0 + mi * 32 + crow(r, h);
;         float a1 = acc[mi][0][r], a3 = acc[mi][1][r];
;         G[(size_t)row * FFH + j] = f2bf(silu_f(a1) * a3);
;       }
	v_add_f32_e32 v144, 1.0, v144
	v_add_f32_e32 v145, 1.0, v145
	v_add_f32_e32 v146, 1.0, v146
	v_add_f32_e32 v147, 1.0, v147
	v_rcp_f32_e32 v144, v144
	v_rcp_f32_e32 v145, v145
	v_rcp_f32_e32 v146, v146
	v_rcp_f32_e32 v147, v147
	s_nop 0
	v_mul_f32_e32 v144, v68, v144
	v_mul_f32_e32 v145, v69, v145
	v_mul_f32_e32 v146, v70, v146
	v_mul_f32_e32 v147, v71, v147
	v_mul_f32_e32 v144, v84, v144
	v_mul_f32_e32 v145, v85, v145
	v_mul_f32_e32 v146, v86, v146
	v_mul_f32_e32 v147, v87, v147
	v_cvt_pk_bf16_f32 v154, v144, v145
	v_cvt_pk_bf16_f32 v155, v146, v147
	s_nop 0
	v_mov_b32_dpp v144, v154 quad_perm:[1,0,3,2] row_mask:0xf bank_mask:0xf
	v_mov_b32_dpp v145, v155 quad_perm:[1,0,3,2] row_mask:0xf bank_mask:0xf
	v_perm_b32 v154, v144, v154, v230
	v_perm_b32 v155, v145, v155, v230
	global_store_dword v148, v154, s[82:83] offset:512
	global_store_dword v148, v155, s[82:83] offset:640
	v_mul_f32_e32 v144, 0xbfb8aa3b, v72
	v_mul_f32_e32 v145, 0xbfb8aa3b, v73
	v_mul_f32_e32 v146, 0xbfb8aa3b, v74
	v_mul_f32_e32 v147, 0xbfb8aa3b, v75
	v_exp_f32_e32 v144, v144
	v_exp_f32_e32 v145, v145
	v_exp_f32_e32 v146, v146
	v_exp_f32_e32 v147, v147
	s_nop 1
	v_add_f32_e32 v144, 1.0, v144
	v_add_f32_e32 v145, 1.0, v145
	v_add_f32_e32 v146, 1.0, v146
	v_add_f32_e32 v147, 1.0, v147
	v_rcp_f32_e32 v144, v144
	v_rcp_f32_e32 v145, v145
	v_rcp_f32_e32 v146, v146
	v_rcp_f32_e32 v147, v147
	s_nop 0
	v_mul_f32_e32 v144, v72, v144
	v_mul_f32_e32 v145, v73, v145
	v_mul_f32_e32 v146, v74, v146
	v_mul_f32_e32 v147, v75, v147
	v_mul_f32_e32 v144, v88, v144
	v_mul_f32_e32 v145, v89, v145
	v_mul_f32_e32 v146, v90, v146
	v_mul_f32_e32 v147, v91, v147
	v_cvt_pk_bf16_f32 v152, v144, v145
	v_cvt_pk_bf16_f32 v153, v146, v147
	s_nop 0
	v_mov_b32_dpp v144, v152 quad_perm:[1,0,3,2] row_mask:0xf bank_mask:0xf
	v_mov_b32_dpp v145, v153 quad_perm:[1,0,3,2] row_mask:0xf bank_mask:0xf
	v_perm_b32 v152, v144, v152, v230
	v_perm_b32 v153, v145, v153, v230
	global_store_dword v148, v152, s[82:83] offset:1024
	global_store_dword v148, v153, s[82:83] offset:1152
	v_mul_f32_e32 v144, 0xbfb8aa3b, v76
	v_mul_f32_e32 v145, 0xbfb8aa3b, v77
	v_mul_f32_e32 v146, 0xbfb8aa3b, v78
	v_mul_f32_e32 v147, 0xbfb8aa3b, v79
	v_exp_f32_e32 v144, v144
	v_exp_f32_e32 v145, v145
	v_exp_f32_e32 v146, v146
	v_exp_f32_e32 v147, v147
	s_nop 1
	v_add_f32_e32 v144, 1.0, v144
	v_add_f32_e32 v145, 1.0, v145
	v_add_f32_e32 v146, 1.0, v146
	v_add_f32_e32 v147, 1.0, v147
	v_rcp_f32_e32 v144, v144
	v_rcp_f32_e32 v145, v145
	v_rcp_f32_e32 v146, v146
	v_rcp_f32_e32 v147, v147
	s_nop 0
	v_mul_f32_e32 v144, v76, v144
	v_mul_f32_e32 v145, v77, v145
	v_mul_f32_e32 v146, v78, v146
	v_mul_f32_e32 v147, v79, v147
	v_mul_f32_e32 v144, v92, v144
	v_mul_f32_e32 v145, v93, v145
	v_mul_f32_e32 v146, v94, v146
	v_mul_f32_e32 v147, v95, v147
	v_cvt_pk_bf16_f32 v154, v144, v145
	v_cvt_pk_bf16_f32 v155, v146, v147
	s_nop 0
	v_mov_b32_dpp v144, v154 quad_perm:[1,0,3,2] row_mask:0xf bank_mask:0xf
	v_mov_b32_dpp v145, v155 quad_perm:[1,0,3,2] row_mask:0xf bank_mask:0xf
	v_perm_b32 v154, v144, v154, v230
	v_perm_b32 v155, v145, v155, v230
	global_store_dword v148, v154, s[82:83] offset:1536
	global_store_dword v148, v155, s[82:83] offset:1664
	v_add_u32_e32 v148, 0x1800, v229
	v_mul_f32_e32 v144, 0xbfb8aa3b, v96
	v_mul_f32_e32 v145, 0xbfb8aa3b, v97
	v_mul_f32_e32 v146, 0xbfb8aa3b, v98
	v_mul_f32_e32 v147, 0xbfb8aa3b, v99
	v_exp_f32_e32 v144, v144
	v_exp_f32_e32 v145, v145
	v_exp_f32_e32 v146, v146
	v_exp_f32_e32 v147, v147
	s_nop 1
	v_add_f32_e32 v144, 1.0, v144
	v_add_f32_e32 v145, 1.0, v145
	v_add_f32_e32 v146, 1.0, v146
	v_add_f32_e32 v147, 1.0, v147
	v_rcp_f32_e32 v144, v144
	v_rcp_f32_e32 v145, v145
	v_rcp_f32_e32 v146, v146
	v_rcp_f32_e32 v147, v147
	s_nop 0
	v_mul_f32_e32 v144, v96, v144
	v_mul_f32_e32 v145, v97, v145
	v_mul_f32_e32 v146, v98, v146
	v_mul_f32_e32 v147, v99, v147
	v_mul_f32_e32 v144, v112, v144
	v_mul_f32_e32 v145, v113, v145
	v_mul_f32_e32 v146, v114, v146
; DI bf16_t f2bf(float x) { return (bf16_t)(pack2(x, x) & 0xffffu); }
; DI int crow(int reg, int h) { return (reg & 3) + 8 * (reg >> 2) + 4 * h; }
; DI float silu_f(float x) { return x * __builtin_amdgcn_rcpf(1.0f + __expf(-x)); }
; template <int EPI>
; DI void epilogue(const Params& p, int layer, f32x16 (&acc)[2][2], int mrow0, int ncol0, int lane) {
;     ...
;   } else if (EPI == EPI_SWIGLU) {
;     bf16_t* G = (bf16_t*)(p.ws + OFF_U);
;     const int j = (ncol0 >> 7) * 64 + ((ncol0 >> 6) & 1) * 32 + c;
; #pragma unroll
;     for (int mi = 0; mi < 2; ++mi)
; #pragma unroll
;       for (int r = 0; r < 16; ++r) {
;         int row = mrow0 + mi * 32 + crow(r, h);
;         float a1 = acc[mi][0][r], a3 = acc[mi][1][r];
;         G[(size_t)row * FFH + j] = f2bf(silu_f(a1) * a3);
;       }
	v_mul_f32_e32 v147, v115, v147
	v_cvt_pk_bf16_f32 v152, v144, v145
	v_cvt_pk_bf16_f32 v153, v146, v147
	s_nop 0
	v_mov_b32_dpp v144, v152 quad_perm:[1,0,3,2] row_mask:0xf bank_mask:0xf
	v_mov_b32_dpp v145, v153 quad_perm:[1,0,3,2] row_mask:0xf bank_mask:0xf
	v_perm_b32 v152, v144, v152, v230
	v_perm_b32 v153, v145, v153, v230
	global_store_dword v148, v152, s[82:83]
	global_store_dword v148, v153, s[82:83] offset:128
	v_mul_f32_e32 v144, 0xbfb8aa3b, v100
	v_mul_f32_e32 v145, 0xbfb8aa3b, v101
	v_mul_f32_e32 v146, 0xbfb8aa3b, v102
	v_mul_f32_e32 v147, 0xbfb8aa3b, v103
	v_exp_f32_e32 v144, v144
	v_exp_f32_e32 v145, v145
	v_exp_f32_e32 v146, v146
	v_exp_f32_e32 v147, v147
	s_nop 1
	v_add_f32_e32 v144, 1.0, v144
	v_add_f32_e32 v145, 1.0, v145
	v_add_f32_e32 v146, 1.0, v146
	v_add_f32_e32 v147, 1.0, v147
	v_rcp_f32_e32 v144, v144
	v_rcp_f32_e32 v145, v145
	v_rcp_f32_e32 v146, v146
	v_rcp_f32_e32 v147, v147
	s_nop 0
	v_mul_f32_e32 v144, v100, v144
	v_mul_f32_e32 v145, v101, v145
	v_mul_f32_e32 v146, v102, v146
	v_mul_f32_e32 v147, v103, v147
	v_mul_f32_e32 v144, v116, v144
	v_mul_f32_e32 v145, v117, v145
	v_mul_f32_e32 v146, v118, v146
	v_mul_f32_e32 v147, v119, v147
	v_cvt_pk_bf16_f32 v154, v144, v145
	v_cvt_pk_bf16_f32 v155, v146, v147
	s_nop 0
	v_mov_b32_dpp v144, v154 quad_perm:[1,0,3,2] row_mask:0xf bank_mask:0xf
	v_mov_b32_dpp v145, v155 quad_perm:[1,0,3,2] row_mask:0xf bank_mask:0xf
	v_perm_b32 v154, v144, v154, v230
	v_perm_b32 v155, v145, v155, v230
	global_store_dword v148, v154, s[82:83] offset:512
	global_store_dword v148, v155, s[82:83] offset:640
	v_mul_f32_e32 v144, 0xbfb8aa3b, v104
	v_mul_f32_e32 v145, 0xbfb8aa3b, v105
	v_mul_f32_e32 v146, 0xbfb8aa3b, v106
	v_mul_f32_e32 v147, 0xbfb8aa3b, v107
	v_exp_f32_e32 v144, v144
	v_exp_f32_e32 v145, v145
	v_exp_f32_e32 v146, v146
	v_exp_f32_e32 v147, v147
	s_nop 1
	v_add_f32_e32 v144, 1.0, v144
	v_add_f32_e32 v145, 1.0, v145
	v_add_f32_e32 v146, 1.0, v146
	v_add_f32_e32 v147, 1.0, v147
	v_rcp_f32_e32 v144, v144
	v_rcp_f32_e32 v145, v145
	v_rcp_f32_e32 v146, v146
	v_rcp_f32_e32 v147, v147
	s_nop 0
	v_mul_f32_e32 v144, v104, v144
	v_mul_f32_e32 v145, v105, v145
	v_mul_f32_e32 v146, v106, v146
	v_mul_f32_e32 v147, v107, v147
	v_mul_f32_e32 v144, v120, v144
	v_mul_f32_e32 v145, v121, v145
	v_mul_f32_e32 v146, v122, v146
	v_mul_f32_e32 v147, v123, v147
	v_cvt_pk_bf16_f32 v152, v144, v145
	v_cvt_pk_bf16_f32 v153, v146, v147
	s_nop 0
	v_mov_b32_dpp v144, v152 quad_perm:[1,0,3,2] row_mask:0xf bank_mask:0xf
	v_mov_b32_dpp v145, v153 quad_perm:[1,0,3,2] row_mask:0xf bank_mask:0xf
	v_perm_b32 v152, v144, v152, v230
	v_perm_b32 v153, v145, v153, v230
	global_store_dword v148, v152, s[82:83] offset:1024
	global_store_dword v148, v153, s[82:83] offset:1152
	v_mul_f32_e32 v144, 0xbfb8aa3b, v108
	v_mul_f32_e32 v145, 0xbfb8aa3b, v109
	v_mul_f32_e32 v146, 0xbfb8aa3b, v110
	v_mul_f32_e32 v147, 0xbfb8aa3b, v111
	v_exp_f32_e32 v144, v144
	v_exp_f32_e32 v145, v145
	v_exp_f32_e32 v146, v146
	v_exp_f32_e32 v147, v147
	s_nop 1
	v_add_f32_e32 v144, 1.0, v144
	v_add_f32_e32 v145, 1.0, v145
	v_add_f32_e32 v146, 1.0, v146
	v_add_f32_e32 v147, 1.0, v147
	v_rcp_f32_e32 v144, v144
	v_rcp_f32_e32 v145, v145
	v_rcp_f32_e32 v146, v146
	v_rcp_f32_e32 v147, v147
	s_nop 0
	v_mul_f32_e32 v144, v108, v144
	v_mul_f32_e32 v145, v109, v145
	v_mul_f32_e32 v146, v110, v146
	v_mul_f32_e32 v147, v111, v147
	v_mul_f32_e32 v144, v124, v144
	v_mul_f32_e32 v145, v125, v145
	v_mul_f32_e32 v146, v126, v146
	v_mul_f32_e32 v147, v127, v147
	v_cvt_pk_bf16_f32 v154, v144, v145
	v_cvt_pk_bf16_f32 v155, v146, v147
	s_nop 0
	v_mov_b32_dpp v144, v154 quad_perm:[1,0,3,2] row_mask:0xf bank_mask:0xf
	v_mov_b32_dpp v145, v155 quad_perm:[1,0,3,2] row_mask:0xf bank_mask:0xf
	v_perm_b32 v154, v144, v154, v230
	v_perm_b32 v155, v145, v155, v230
	global_store_dword v148, v154, s[82:83] offset:1536
	global_store_dword v148, v155, s[82:83] offset:1664
	s_branch .Lmg_next
